# sb queue grab issued one unit ahead (atomic round trip hidden behind the unit body)
# speedup vs baseline: 1.0010x; 1.0010x over previous
.LBB0_352:
	s_or_b64 exec, exec, s[0:1]
	v_readfirstlane_b32 s2, v0
	s_cmpk_gt_i32 s2, 0x1ff
	s_cbranch_scc1 .LBB0_361
	s_add_u32 s10, s54, 0x2a080000
	s_addc_u32 s11, s55, 0
	s_add_u32 s14, s54, 0x2c080000
	s_addc_u32 s15, s55, 0
	s_add_u32 s16, s54, 0x2b080000
	s_addc_u32 s17, s55, 0
	v_mov_b32_e32 v204, 1
	s_mov_b64 exec, 1
	global_atomic_add v203, v65, v204, s[8:9] sc0
	s_mov_b64 exec, -1
.LBB0_354:
.LBB0_358:
	s_or_b64 exec, exec, s[0:1]
	s_lshr_b32 s3, s2, 6
	s_and_b32 s0, s2, 63
	s_sub_i32 s12, 63, s0
	v_readlane_b32 s0, v253, 31
	v_and_b32_e32 v152, 31, v186
	v_bfe_u32 v153, v186, 5, 1
	s_lshl_b32 s1, s0, 2
	s_add_i32 s1, s1, s3
	s_lshl_b32 s1, s1, 18
	s_add_u32 s40, s16, s1
	s_addc_u32 s41, s17, 0
	s_add_u32 s42, s14, s1
	s_addc_u32 s43, s15, 0
	s_lshl_b32 s1, s0, 10
	s_lshl_b32 s4, s12, 5
	s_add_i32 s1, s1, s4
	v_add_u32_e32 v154, s1, v152
	v_lshlrev_b32_e32 v155, 10, v154
	v_lshl_add_u32 v155, v153, 4, v155
	s_lshl_b32 s1, s3, 7
	s_add_u32 s4, s10, s1
	s_addc_u32 s5, s11, 0
	global_load_dwordx4 v[48:51], v155, s[4:5]
	global_load_dwordx4 v[52:55], v155, s[4:5] offset:32
	global_load_dwordx4 v[56:59], v155, s[4:5] offset:64
	global_load_dwordx4 v[60:63], v155, s[4:5] offset:96
	v_and_b32_e32 v200, 63, v186
	v_lshlrev_b32_e32 v200, 4, v200
	v_lshlrev_b32_e32 v201, 5, v152
	v_lshl_add_u32 v201, v153, 4, v201
	s_lshl_b32 s1, s12, 12
	s_add_u32 s4, s40, s1
	s_addc_u32 s5, s41, 0
	global_load_dwordx4 v[66:69], v200, s[4:5]
	global_load_dwordx4 v[70:73], v200, s[4:5] offset:1024
	global_load_dwordx4 v[74:77], v200, s[4:5] offset:2048
	global_load_dwordx4 v[78:81], v200, s[4:5] offset:3072
	v_xor_b32_e32 v114, 32, v190
	v_lshlrev_b32_e32 v114, 2, v114
	v_lshlrev_b32_e32 v115, 2, v153
	v_sub_u32_e32 v115, v152, v115
	v_sub_u32_e32 v116, 1, v153
	v_sub_u32_e32 v116, 0, v116
	v_lshlrev_b32_e32 v156, 13, v154
	v_lshl_add_u32 v156, v153, 4, v156
	s_lshl_b32 s1, s3, 8
	s_add_i32 s1, s1, 0x1800
	v_add_u32_e32 v156, s1, v156
	s_add_u32 s4, s54, 0x20000000
	s_addc_u32 s5, s55, 0
	v_mov_b32_e32 v161, s5
	v_add_co_u32_e32 v160, vcc, s4, v156
	s_nop 1
	v_addc_co_u32_e32 v161, vcc, 0, v161, vcc
	v_mov_b32_e32 v127, 0
	v_mov_b32_e32 v0, 0
	v_mov_b32_e32 v1, 0
	v_mov_b32_e32 v2, 0
	v_mov_b32_e32 v3, 0
	v_mov_b32_e32 v4, 0
	v_mov_b32_e32 v5, 0
	v_mov_b32_e32 v6, 0
	v_mov_b32_e32 v7, 0
	v_mov_b32_e32 v8, 0
	v_mov_b32_e32 v9, 0
	v_mov_b32_e32 v10, 0
	v_mov_b32_e32 v11, 0
	v_mov_b32_e32 v12, 0
	v_mov_b32_e32 v13, 0
	v_mov_b32_e32 v14, 0
	v_mov_b32_e32 v15, 0
	v_mov_b32_e32 v16, 0
	v_mov_b32_e32 v17, 0
	v_mov_b32_e32 v18, 0
	v_mov_b32_e32 v19, 0
	v_mov_b32_e32 v20, 0
	v_mov_b32_e32 v21, 0
	v_mov_b32_e32 v22, 0
	v_mov_b32_e32 v23, 0
	v_mov_b32_e32 v24, 0
	v_mov_b32_e32 v25, 0
	v_mov_b32_e32 v26, 0
	v_mov_b32_e32 v27, 0
	v_mov_b32_e32 v28, 0
	v_mov_b32_e32 v29, 0
	v_mov_b32_e32 v30, 0
	v_mov_b32_e32 v31, 0
	s_sub_i32 s0, s12, 1
	s_max_i32 s0, s0, 0
	s_lshl_b32 s0, s0, 12
	s_add_u32 s2, s40, s0
	s_addc_u32 s3, s41, 0
	s_lshl_b32 s0, s12, 12
	s_add_u32 s18, s42, s0
	s_addc_u32 s19, s43, 0
	s_waitcnt vmcnt(0)
	global_load_dwordx4 v[82:85], v200, s[2:3]
	global_load_dwordx4 v[86:89], v200, s[2:3] offset:1024
	global_load_dwordx4 v[90:93], v200, s[2:3] offset:2048
	global_load_dwordx4 v[94:97], v200, s[2:3] offset:3072
	global_load_dwordx4 v[98:101], v201, s[18:19]
	global_load_dwordx4 v[102:105], v201, s[18:19] offset:1024
	global_load_dwordx4 v[106:109], v201, s[18:19] offset:2048
	global_load_dwordx4 v[110:113], v201, s[18:19] offset:3072
	v_mfma_f32_32x32x16_bf16 v[32:47], v[66:69], v[48:51], 0
	v_mfma_f32_32x32x16_bf16 v[32:47], v[70:73], v[52:55], v[32:47]
	v_mfma_f32_32x32x16_bf16 v[32:47], v[74:77], v[56:59], v[32:47]
	v_mfma_f32_32x32x16_bf16 v[32:47], v[78:81], v[60:63], v[32:47]
	s_nop 11
	v_mul_f32_e32 v44, 0x3fb8aa3b, v44
	v_mul_f32_e32 v45, 0x3fb8aa3b, v45
	v_mul_f32_e32 v46, 0x3fb8aa3b, v46
	v_mul_f32_e32 v47, 0x3fb8aa3b, v47
	v_exp_f32_e64 v152, -|v44|
	v_exp_f32_e64 v153, -|v45|
	v_exp_f32_e64 v154, -|v46|
	v_exp_f32_e64 v155, -|v47|
	v_max_f32_e32 v140, 0, v44
	v_max_f32_e32 v141, 0, v45
	v_max_f32_e32 v142, 0, v46
	v_max_f32_e32 v143, 0, v47
	v_add_f32_e32 v152, 1.0, v152
	v_add_f32_e32 v153, 1.0, v153
	v_add_f32_e32 v154, 1.0, v154
	v_add_f32_e32 v155, 1.0, v155
	v_log_f32_e32 v152, v152
	v_log_f32_e32 v153, v153
	v_log_f32_e32 v154, v154
	v_log_f32_e32 v155, v155
	s_nop 0
	v_add_f32_e32 v140, v140, v152
	v_add_f32_e32 v141, v141, v153
	v_add_f32_e32 v142, v142, v154
	v_add_f32_e32 v143, v143, v155
	v_cmp_lt_i32_e64 s[0:1], 24, v115
	v_cmp_lt_i32_e64 s[2:3], 25, v115
	v_cmp_lt_i32_e64 s[4:5], 26, v115
	v_cmp_lt_i32_e64 s[6:7], 27, v115
	s_nop 1
	v_cndmask_b32_e64 v140, 0, v140, s[0:1]
	v_cndmask_b32_e64 v141, 0, v141, s[2:3]
	v_cndmask_b32_e64 v142, 0, v142, s[4:5]
	v_cndmask_b32_e64 v143, 0, v143, s[6:7]
	v_add_f32_e32 v152, v140, v141
	v_add_f32_e32 v153, v142, v143
	v_add_f32_e32 v122, v152, v153
	ds_bpermute_b32 v126, v114, v122
	v_mul_f32_e32 v40, 0x3fb8aa3b, v40
	v_mul_f32_e32 v41, 0x3fb8aa3b, v41
	v_mul_f32_e32 v42, 0x3fb8aa3b, v42
	v_mul_f32_e32 v43, 0x3fb8aa3b, v43
	v_exp_f32_e64 v152, -|v40|
	v_exp_f32_e64 v153, -|v41|
	v_exp_f32_e64 v154, -|v42|
	v_exp_f32_e64 v155, -|v43|
	v_max_f32_e32 v136, 0, v40
	v_max_f32_e32 v137, 0, v41
	v_max_f32_e32 v138, 0, v42
	v_max_f32_e32 v139, 0, v43
	v_add_f32_e32 v152, 1.0, v152
	v_add_f32_e32 v153, 1.0, v153
	v_add_f32_e32 v154, 1.0, v154
	v_add_f32_e32 v155, 1.0, v155
	v_log_f32_e32 v152, v152
	v_log_f32_e32 v153, v153
	v_log_f32_e32 v154, v154
	v_log_f32_e32 v155, v155
	s_nop 0
	v_add_f32_e32 v136, v136, v152
	v_add_f32_e32 v137, v137, v153
	v_add_f32_e32 v138, v138, v154
	v_add_f32_e32 v139, v139, v155
	v_cmp_lt_i32_e64 s[0:1], 16, v115
	v_cmp_lt_i32_e64 s[2:3], 17, v115
	v_cmp_lt_i32_e64 s[4:5], 18, v115
	v_cmp_lt_i32_e64 s[6:7], 19, v115
	s_nop 1
	v_cndmask_b32_e64 v136, 0, v136, s[0:1]
	v_cndmask_b32_e64 v137, 0, v137, s[2:3]
	v_cndmask_b32_e64 v138, 0, v138, s[4:5]
	v_cndmask_b32_e64 v139, 0, v139, s[6:7]
	v_add_f32_e32 v152, v136, v137
	v_add_f32_e32 v153, v138, v139
	v_add_f32_e32 v121, v152, v153
	ds_bpermute_b32 v125, v114, v121
	v_mul_f32_e32 v36, 0x3fb8aa3b, v36
	v_mul_f32_e32 v37, 0x3fb8aa3b, v37
	v_mul_f32_e32 v38, 0x3fb8aa3b, v38
	v_mul_f32_e32 v39, 0x3fb8aa3b, v39
	v_exp_f32_e64 v152, -|v36|
	v_exp_f32_e64 v153, -|v37|
	v_exp_f32_e64 v154, -|v38|
	v_exp_f32_e64 v155, -|v39|
	v_max_f32_e32 v132, 0, v36
	v_max_f32_e32 v133, 0, v37
	v_max_f32_e32 v134, 0, v38
	v_max_f32_e32 v135, 0, v39
	v_add_f32_e32 v152, 1.0, v152
	v_add_f32_e32 v153, 1.0, v153
	v_add_f32_e32 v154, 1.0, v154
	v_add_f32_e32 v155, 1.0, v155
	v_log_f32_e32 v152, v152
	v_log_f32_e32 v153, v153
	v_log_f32_e32 v154, v154
	v_log_f32_e32 v155, v155
	s_nop 0
	v_add_f32_e32 v132, v132, v152
	v_add_f32_e32 v133, v133, v153
	v_add_f32_e32 v134, v134, v154
	v_add_f32_e32 v135, v135, v155
	v_cmp_lt_i32_e64 s[0:1], 8, v115
	v_cmp_lt_i32_e64 s[2:3], 9, v115
	v_cmp_lt_i32_e64 s[4:5], 10, v115
	v_cmp_lt_i32_e64 s[6:7], 11, v115
	s_nop 1
	v_cndmask_b32_e64 v132, 0, v132, s[0:1]
	v_cndmask_b32_e64 v133, 0, v133, s[2:3]
	v_cndmask_b32_e64 v134, 0, v134, s[4:5]
	v_cndmask_b32_e64 v135, 0, v135, s[6:7]
	v_add_f32_e32 v152, v132, v133
	v_add_f32_e32 v153, v134, v135
	v_add_f32_e32 v120, v152, v153
	ds_bpermute_b32 v124, v114, v120
	v_mul_f32_e32 v32, 0x3fb8aa3b, v32
	v_mul_f32_e32 v33, 0x3fb8aa3b, v33
	v_mul_f32_e32 v34, 0x3fb8aa3b, v34
	v_mul_f32_e32 v35, 0x3fb8aa3b, v35
	v_exp_f32_e64 v152, -|v32|
	v_exp_f32_e64 v153, -|v33|
	v_exp_f32_e64 v154, -|v34|
	v_exp_f32_e64 v155, -|v35|
	v_max_f32_e32 v128, 0, v32
	v_max_f32_e32 v129, 0, v33
	v_max_f32_e32 v130, 0, v34
	v_max_f32_e32 v131, 0, v35
	v_add_f32_e32 v152, 1.0, v152
	v_add_f32_e32 v153, 1.0, v153
	v_add_f32_e32 v154, 1.0, v154
	v_add_f32_e32 v155, 1.0, v155
	v_log_f32_e32 v152, v152
	v_log_f32_e32 v153, v153
	v_log_f32_e32 v154, v154
	v_log_f32_e32 v155, v155
	s_nop 0
	v_add_f32_e32 v128, v128, v152
	v_add_f32_e32 v129, v129, v153
	v_add_f32_e32 v130, v130, v154
	v_add_f32_e32 v131, v131, v155
	v_cmp_lt_i32_e64 s[0:1], 0, v115
	v_cmp_lt_i32_e64 s[2:3], 1, v115
	v_cmp_lt_i32_e64 s[4:5], 2, v115
	v_cmp_lt_i32_e64 s[6:7], 3, v115
	s_nop 1
	v_cndmask_b32_e64 v128, 0, v128, s[0:1]
	v_cndmask_b32_e64 v129, 0, v129, s[2:3]
	v_cndmask_b32_e64 v130, 0, v130, s[4:5]
	v_cndmask_b32_e64 v131, 0, v131, s[6:7]
	v_add_f32_e32 v152, v128, v129
	v_add_f32_e32 v153, v130, v131
	v_add_f32_e32 v119, v152, v153
	ds_bpermute_b32 v123, v114, v119
	s_waitcnt lgkmcnt(3)
	v_and_b32_e32 v152, v116, v126
	v_add_f32_e32 v153, v122, v126
	v_sub_f32_e32 v199, v127, v152
	v_sub_f32_e32 v127, v127, v153
	v_sub_f32_e32 v159, v199, v143
	v_sub_f32_e32 v158, v159, v142
	v_sub_f32_e32 v157, v158, v141
	v_sub_f32_e32 v156, v157, v140
	v_cmp_lt_i32_e64 s[0:1], 24, v115
	v_cmp_lt_i32_e64 s[2:3], 25, v115
	v_cmp_lt_i32_e64 s[4:5], 26, v115
	v_cmp_lt_i32_e64 s[6:7], 27, v115
	v_add_f32_e32 v44, v44, v156
	v_add_f32_e32 v45, v45, v157
	v_add_f32_e32 v46, v46, v158
	v_add_f32_e32 v47, v47, v159
	v_exp_f32_e32 v44, v44
	v_exp_f32_e32 v45, v45
	v_exp_f32_e32 v46, v46
	v_exp_f32_e32 v47, v47
	s_nop 0
	v_cndmask_b32_e64 v44, 0, v44, s[0:1]
	v_cndmask_b32_e64 v45, 0, v45, s[2:3]
	v_cndmask_b32_e64 v46, 0, v46, s[4:5]
	v_cndmask_b32_e64 v47, 0, v47, s[6:7]
	s_waitcnt lgkmcnt(2)
	v_and_b32_e32 v152, v116, v125
	v_add_f32_e32 v153, v121, v125
	v_sub_f32_e32 v199, v127, v152
	v_sub_f32_e32 v127, v127, v153
	v_sub_f32_e32 v159, v199, v139
	v_sub_f32_e32 v158, v159, v138
	v_sub_f32_e32 v157, v158, v137
	v_sub_f32_e32 v156, v157, v136
	v_cmp_lt_i32_e64 s[0:1], 16, v115
	v_cmp_lt_i32_e64 s[2:3], 17, v115
	v_cmp_lt_i32_e64 s[4:5], 18, v115
	v_cmp_lt_i32_e64 s[6:7], 19, v115
	v_add_f32_e32 v40, v40, v156
	v_add_f32_e32 v41, v41, v157
	v_add_f32_e32 v42, v42, v158
	v_add_f32_e32 v43, v43, v159
	v_exp_f32_e32 v40, v40
	v_exp_f32_e32 v41, v41
	v_exp_f32_e32 v42, v42
	v_exp_f32_e32 v43, v43
	s_nop 0
	v_cndmask_b32_e64 v40, 0, v40, s[0:1]
	v_cndmask_b32_e64 v41, 0, v41, s[2:3]
	v_cndmask_b32_e64 v42, 0, v42, s[4:5]
	v_cndmask_b32_e64 v43, 0, v43, s[6:7]
	s_waitcnt lgkmcnt(1)
	v_and_b32_e32 v152, v116, v124
	v_add_f32_e32 v153, v120, v124
	v_sub_f32_e32 v199, v127, v152
	v_sub_f32_e32 v127, v127, v153
	v_sub_f32_e32 v159, v199, v135
	v_sub_f32_e32 v158, v159, v134
	v_sub_f32_e32 v157, v158, v133
	v_sub_f32_e32 v156, v157, v132
	v_cmp_lt_i32_e64 s[0:1], 8, v115
	v_cmp_lt_i32_e64 s[2:3], 9, v115
	v_cmp_lt_i32_e64 s[4:5], 10, v115
	v_cmp_lt_i32_e64 s[6:7], 11, v115
	v_add_f32_e32 v36, v36, v156
	v_add_f32_e32 v37, v37, v157
	v_add_f32_e32 v38, v38, v158
	v_add_f32_e32 v39, v39, v159
	v_exp_f32_e32 v36, v36
	v_exp_f32_e32 v37, v37
	v_exp_f32_e32 v38, v38
	v_exp_f32_e32 v39, v39
	s_nop 0
	v_cndmask_b32_e64 v36, 0, v36, s[0:1]
	v_cndmask_b32_e64 v37, 0, v37, s[2:3]
	v_cndmask_b32_e64 v38, 0, v38, s[4:5]
	v_cndmask_b32_e64 v39, 0, v39, s[6:7]
	s_waitcnt lgkmcnt(0)
	v_and_b32_e32 v152, v116, v123
	v_add_f32_e32 v153, v119, v123
	v_sub_f32_e32 v199, v127, v152
	v_sub_f32_e32 v127, v127, v153
	v_sub_f32_e32 v159, v199, v131
	v_sub_f32_e32 v158, v159, v130
	v_sub_f32_e32 v157, v158, v129
	v_sub_f32_e32 v156, v157, v128
	v_cmp_lt_i32_e64 s[0:1], 0, v115
	v_cmp_lt_i32_e64 s[2:3], 1, v115
	v_cmp_lt_i32_e64 s[4:5], 2, v115
	v_cmp_lt_i32_e64 s[6:7], 3, v115
	v_add_f32_e32 v32, v32, v156
	v_add_f32_e32 v33, v33, v157
	v_add_f32_e32 v34, v34, v158
	v_add_f32_e32 v35, v35, v159
	v_exp_f32_e32 v32, v32
	v_exp_f32_e32 v33, v33
	v_exp_f32_e32 v34, v34
	v_exp_f32_e32 v35, v35
	s_nop 0
	v_cndmask_b32_e64 v32, 0, v32, s[0:1]
	v_cndmask_b32_e64 v33, 0, v33, s[2:3]
	v_cndmask_b32_e64 v34, 0, v34, s[4:5]
	v_cndmask_b32_e64 v35, 0, v35, s[6:7]
	v_cvt_pk_bf16_f32 v144, v32, v33
	v_cvt_pk_bf16_f32 v145, v34, v35
	v_cvt_pk_bf16_f32 v146, v36, v37
	v_cvt_pk_bf16_f32 v147, v38, v39
	v_cvt_pk_bf16_f32 v148, v40, v41
	v_cvt_pk_bf16_f32 v149, v42, v43
	v_cvt_pk_bf16_f32 v150, v44, v45
	v_cvt_pk_bf16_f32 v151, v46, v47
	v_cmp_gt_f32_e32 vcc, 0xc3177ba5, v127
	s_waitcnt vmcnt(0)
	v_mfma_f32_32x32x16_bf16 v[16:31], v[98:101], v[144:147], v[16:31]
	v_mfma_f32_32x32x16_bf16 v[0:15], v[102:105], v[144:147], v[0:15]
	v_mfma_f32_32x32x16_bf16 v[16:31], v[106:109], v[148:151], v[16:31]
	v_mfma_f32_32x32x16_bf16 v[0:15], v[110:113], v[148:151], v[0:15]
	s_cmp_eq_u64 vcc, exec
	s_cselect_b32 s0, 1, 0
	s_cmp_eq_u32 s12, 0
	s_cselect_b32 s1, 1, 0
	s_or_b32 s0, s0, s1
	s_sub_i32 s12, s12, 1
	s_cmp_lg_u32 s0, 0
	s_cbranch_scc1 .Lsb_done

.Lsb_done:
	v_readfirstlane_b32 s2, v203
	s_nop 7
	s_nop 2
	global_store_dwordx4 v[160:161], v[16:19], off
	global_store_dwordx4 v[160:161], v[20:23], off offset:32
	global_store_dwordx4 v[160:161], v[24:27], off offset:64
	global_store_dwordx4 v[160:161], v[28:31], off offset:96
	global_store_dwordx4 v[160:161], v[0:3], off offset:128
	global_store_dwordx4 v[160:161], v[4:7], off offset:160
	global_store_dwordx4 v[160:161], v[8:11], off offset:192
	global_store_dwordx4 v[160:161], v[12:15], off offset:224
	s_cmpk_gt_i32 s2, 0x1ff
	s_cbranch_scc1 .Lsb_exit
	s_mov_b64 exec, 1
	global_atomic_add v203, v65, v204, s[8:9] sc0
	s_mov_b64 exec, -1
	s_branch .LBB0_354
.Lsb_exit:
.LBB0_361:
	s_mov_b64 s[0:1], 0
